# MLA loop variant: softmax VALU weighted toward later MFMA slots of each tile
# speedup vs baseline: 1.0087x; 1.0087x over previous
.Lmf_loop:
	ds_read_b128 v[162:165], v216 offset:13312
	ds_read_b128 v[166:169], v216 offset:19968
	ds_read_b128 v[172:175], v216 offset:13344
	ds_read_b128 v[176:179], v216 offset:20000
	ds_read_b128 v[180:183], v216 offset:13376
	global_load_dwordx4 v[130:133], v235, s[14:15]
	global_load_dwordx4 v[134:137], v236, s[14:15]
	s_add_u32 s14, s14, 0x18000
	s_addc_u32 s15, s15, 0
	global_load_dwordx4 v[142:145], v237, s[12:13]
	s_add_u32 s12, s12, 0x80
	s_addc_u32 s13, s13, 0
	s_waitcnt lgkmcnt(4)
	v_mfma_f32_32x32x16_bf16 v[34:49], v[162:165], v[98:101], v[146:161]
	ds_read_b128 v[184:187], v216 offset:20032
	v_exp_f32_e32 v66, v66
	v_exp_f32_e32 v67, v67
	s_waitcnt lgkmcnt(4)
	v_mfma_f32_32x32x16_bf16 v[50:65], v[166:169], v[98:101], v[146:161]
	ds_read_b128 v[188:191], v216 offset:13408
	v_exp_f32_e32 v68, v68
	v_exp_f32_e32 v69, v69
	s_waitcnt lgkmcnt(4)
	v_mfma_f32_32x32x16_bf16 v[34:49], v[172:175], v[102:105], v[34:49]
	ds_read_b128 v[192:195], v216 offset:20064
	v_add_f32_e32 v171, v66, v171
	v_exp_f32_e32 v70, v70
	v_exp_f32_e32 v71, v71
	s_waitcnt lgkmcnt(4)
	v_mfma_f32_32x32x16_bf16 v[50:65], v[176:179], v[102:105], v[50:65]
	ds_read_b128 v[162:165], v216 offset:13440
	v_add_f32_e32 v171, v68, v171
	v_exp_f32_e32 v72, v72
	v_add_f32_e32 v197, v67, v69
	v_exp_f32_e32 v73, v73
	s_waitcnt lgkmcnt(4)
	v_mfma_f32_32x32x16_bf16 v[34:49], v[180:183], v[106:109], v[34:49]
	ds_read_b128 v[166:169], v216 offset:20096
	v_add_f32_e32 v171, v70, v171
	v_add_f32_e32 v197, v71, v197
	v_cvt_pk_bf16_f32 v66, v66, v67
	v_add_f32_e32 v171, v72, v171
	v_cvt_pk_bf16_f32 v67, v68, v69
	s_waitcnt lgkmcnt(4)
	v_mfma_f32_32x32x16_bf16 v[50:65], v[184:187], v[106:109], v[50:65]
	ds_read_b128 v[172:175], v216 offset:13472
	v_add_f32_e32 v197, v73, v197
	v_cvt_pk_bf16_f32 v68, v70, v71
	v_cvt_pk_bf16_f32 v69, v72, v73
	v_exp_f32_e32 v74, v74
	v_exp_f32_e32 v75, v75
	s_waitcnt lgkmcnt(4)
	v_mfma_f32_32x32x16_bf16 v[34:49], v[188:191], v[110:113], v[34:49]
	ds_read_b128 v[176:179], v216 offset:20128
	v_exp_f32_e32 v76, v76
	v_exp_f32_e32 v77, v77
	v_add_f32_e32 v171, v74, v171
	s_waitcnt lgkmcnt(4)
	v_mfma_f32_32x32x16_bf16 v[50:65], v[192:195], v[110:113], v[50:65]
	ds_read_b128 v[180:183], v217 offset:26624
	v_exp_f32_e32 v78, v78
	v_add_f32_e32 v197, v75, v197
	v_exp_f32_e32 v79, v79
	v_add_f32_e32 v171, v76, v171
	s_waitcnt lgkmcnt(4)
	v_mfma_f32_32x32x16_bf16 v[34:49], v[162:165], v[114:117], v[34:49]
	ds_read_b128 v[184:187], v217 offset:31232
	v_exp_f32_e32 v80, v80
	v_add_f32_e32 v197, v77, v197
	v_exp_f32_e32 v81, v81
	v_add_f32_e32 v171, v78, v171
	v_add_f32_e32 v197, v79, v197
	s_waitcnt lgkmcnt(4)
	v_mfma_f32_32x32x16_bf16 v[50:65], v[166:169], v[114:117], v[50:65]
	ds_read_b128 v[188:191], v217 offset:26656
	v_cvt_pk_bf16_f32 v74, v74, v75
	v_add_f32_e32 v171, v80, v171
	v_cvt_pk_bf16_f32 v75, v76, v77
	v_add_f32_e32 v197, v81, v197
	v_cvt_pk_bf16_f32 v76, v78, v79
	v_cvt_pk_bf16_f32 v77, v80, v81
	v_exp_f32_e32 v82, v82
	s_waitcnt lgkmcnt(4)
	v_mfma_f32_32x32x16_bf16 v[34:49], v[172:175], v[118:121], v[34:49]
	ds_read_b128 v[192:195], v217 offset:31264
	v_exp_f32_e32 v83, v83
	v_exp_f32_e32 v84, v84
	v_exp_f32_e32 v85, v85
	s_waitcnt lgkmcnt(4)
	v_mfma_f32_32x32x16_bf16 v[50:65], v[176:179], v[118:121], v[50:65]
	ds_read_b128 v[162:165], v217 offset:26688
	v_add_f32_e32 v171, v82, v171
	v_exp_f32_e32 v86, v86
	v_add_f32_e32 v197, v83, v197
	v_exp_f32_e32 v87, v87
	v_add_f32_e32 v171, v84, v171
	s_waitcnt lgkmcnt(4)
	v_mfma_f32_32x32x16_bf16 v[18:33], v[180:183], v[66:69], v[18:33]
	ds_read_b128 v[166:169], v217 offset:31296
	v_exp_f32_e32 v88, v88
	v_add_f32_e32 v197, v85, v197
	v_exp_f32_e32 v89, v89
	v_add_f32_e32 v171, v86, v171
	v_add_f32_e32 v197, v87, v197
	s_waitcnt lgkmcnt(4)
	v_mfma_f32_32x32x16_bf16 v[2:17], v[184:187], v[66:69], v[2:17]
	ds_read_b128 v[172:175], v217 offset:26720
	v_cvt_pk_bf16_f32 v82, v82, v83
	v_add_f32_e32 v171, v88, v171
	v_cvt_pk_bf16_f32 v83, v84, v85
	v_add_f32_e32 v197, v89, v197
	v_cvt_pk_bf16_f32 v84, v86, v87
	v_cvt_pk_bf16_f32 v85, v88, v89
	v_exp_f32_e32 v90, v90
	s_waitcnt lgkmcnt(4)
	v_mfma_f32_32x32x16_bf16 v[18:33], v[188:191], v[74:77], v[18:33]
	ds_read_b128 v[176:179], v217 offset:31328
	v_exp_f32_e32 v91, v91
	v_exp_f32_e32 v92, v92
	v_exp_f32_e32 v93, v93
	v_add_f32_e32 v171, v90, v171
	s_waitcnt lgkmcnt(4)
	v_mfma_f32_32x32x16_bf16 v[2:17], v[192:195], v[74:77], v[2:17]
	s_waitcnt vmcnt(3)
	v_add_u32_e32 v196, 0x8800, v215
	ds_write_b128 v228, v[122:125]
	ds_write_b128 v238, v[126:129]
	ds_write2_b64 v196, v[138:139], v[140:141] offset0:128 offset1:130
	v_exp_f32_e32 v94, v94
	v_add_f32_e32 v197, v91, v197
	v_exp_f32_e32 v95, v95
	v_add_f32_e32 v171, v92, v171
	v_exp_f32_e32 v96, v96
	s_waitcnt lgkmcnt(6)
	v_mfma_f32_32x32x16_bf16 v[18:33], v[162:165], v[82:85], v[18:33]
	v_add_f32_e32 v197, v93, v197
	v_exp_f32_e32 v97, v97
	v_add_f32_e32 v171, v94, v171
	v_add_f32_e32 v197, v95, v197
	v_cvt_pk_bf16_f32 v90, v90, v91
	v_add_f32_e32 v171, v96, v171
	v_cvt_pk_bf16_f32 v91, v92, v93
	s_waitcnt lgkmcnt(5)
	v_mfma_f32_32x32x16_bf16 v[2:17], v[166:169], v[82:85], v[2:17]
	v_add_f32_e32 v197, v97, v197
	v_cvt_pk_bf16_f32 v92, v94, v95
	v_cvt_pk_bf16_f32 v93, v96, v97
	v_max3_f32 v1, v34, v35, v36
	v_max3_f32 v170, v37, v38, v39
	v_max3_f32 v1, v1, v40, v41
	v_max3_f32 v170, v170, v42, v43
	v_max3_f32 v1, v1, v44, v45
	s_waitcnt lgkmcnt(4)
	v_mfma_f32_32x32x16_bf16 v[18:33], v[172:175], v[90:93], v[18:33]
	v_max3_f32 v170, v170, v46, v47
	v_max3_f32 v1, v1, v48, v49
	v_max3_f32 v170, v170, v50, v51
	v_max3_f32 v1, v1, v52, v53
	v_max3_f32 v170, v170, v54, v55
	v_max3_f32 v1, v1, v56, v57
	v_max3_f32 v170, v170, v58, v59
	v_max3_f32 v1, v1, v60, v61
	s_waitcnt lgkmcnt(3)
	v_mfma_f32_32x32x16_bf16 v[2:17], v[176:179], v[90:93], v[2:17]
	v_max3_f32 v170, v170, v62, v63
	v_max3_f32 v1, v1, v64, v65
	v_max_f32_e32 v1, v1, v170
	v_mov_b32_e32 v170, v1
	v_add_f32_e32 v171, v197, v171
	s_nop 0
	v_permlane32_swap_b32_e32 v1, v170
	v_max_f32_e32 v1, v1, v170
	v_cmp_lt_f32_e32 vcc, s93, v1
	s_cbranch_vccnz .Lmf_slow_0
.Lmf_join_0:
	s_waitcnt lgkmcnt(0)
	s_barrier
	ds_read_b128 v[162:165], v216 offset:0
	ds_read_b128 v[166:169], v216 offset:6656
	ds_read_b128 v[172:175], v216 offset:32
	ds_read_b128 v[176:179], v216 offset:6688
	ds_read_b128 v[180:183], v216 offset:64
	global_load_dwordx4 v[122:125], v235, s[14:15]
	global_load_dwordx4 v[126:129], v236, s[14:15]
	s_add_u32 s14, s14, 0x18000
	s_addc_u32 s15, s15, 0
	global_load_dwordx4 v[138:141], v237, s[12:13]
	s_add_u32 s12, s12, 0x80
	s_addc_u32 s13, s13, 0
	s_waitcnt lgkmcnt(4)
	v_mfma_f32_32x32x16_bf16 v[66:81], v[162:165], v[98:101], v[146:161]
	ds_read_b128 v[184:187], v216 offset:6720
	v_exp_f32_e32 v34, v34
	v_exp_f32_e32 v35, v35
	s_waitcnt lgkmcnt(4)
	v_mfma_f32_32x32x16_bf16 v[82:97], v[166:169], v[98:101], v[146:161]
	ds_read_b128 v[188:191], v216 offset:96
	v_exp_f32_e32 v36, v36
	v_exp_f32_e32 v37, v37
	s_waitcnt lgkmcnt(4)
	v_mfma_f32_32x32x16_bf16 v[66:81], v[172:175], v[102:105], v[66:81]
	ds_read_b128 v[192:195], v216 offset:6752
	v_add_f32_e32 v171, v34, v171
	v_exp_f32_e32 v38, v38
	v_exp_f32_e32 v39, v39
	s_waitcnt lgkmcnt(4)
	v_mfma_f32_32x32x16_bf16 v[82:97], v[176:179], v[102:105], v[82:97]
	ds_read_b128 v[162:165], v216 offset:128
	v_add_f32_e32 v171, v36, v171
	v_exp_f32_e32 v40, v40
	v_add_f32_e32 v197, v35, v37
	v_exp_f32_e32 v41, v41
	s_waitcnt lgkmcnt(4)
	v_mfma_f32_32x32x16_bf16 v[66:81], v[180:183], v[106:109], v[66:81]
	ds_read_b128 v[166:169], v216 offset:6784
	v_add_f32_e32 v171, v38, v171
	v_add_f32_e32 v197, v39, v197
	v_cvt_pk_bf16_f32 v34, v34, v35
	v_add_f32_e32 v171, v40, v171
	v_cvt_pk_bf16_f32 v35, v36, v37
	s_waitcnt lgkmcnt(4)
	v_mfma_f32_32x32x16_bf16 v[82:97], v[184:187], v[106:109], v[82:97]
	ds_read_b128 v[172:175], v216 offset:160
	v_add_f32_e32 v197, v41, v197
	v_cvt_pk_bf16_f32 v36, v38, v39
	v_cvt_pk_bf16_f32 v37, v40, v41
	v_exp_f32_e32 v42, v42
	v_exp_f32_e32 v43, v43
	s_waitcnt lgkmcnt(4)
	v_mfma_f32_32x32x16_bf16 v[66:81], v[188:191], v[110:113], v[66:81]
	ds_read_b128 v[176:179], v216 offset:6816
	v_exp_f32_e32 v44, v44
	v_exp_f32_e32 v45, v45
	v_add_f32_e32 v171, v42, v171
	s_waitcnt lgkmcnt(4)
	v_mfma_f32_32x32x16_bf16 v[82:97], v[192:195], v[110:113], v[82:97]
	ds_read_b128 v[180:183], v217 offset:35840
	v_exp_f32_e32 v46, v46
	v_add_f32_e32 v197, v43, v197
	v_exp_f32_e32 v47, v47
	v_add_f32_e32 v171, v44, v171
	s_waitcnt lgkmcnt(4)
	v_mfma_f32_32x32x16_bf16 v[66:81], v[162:165], v[114:117], v[66:81]
	ds_read_b128 v[184:187], v217 offset:40448
	v_exp_f32_e32 v48, v48
	v_add_f32_e32 v197, v45, v197
	v_exp_f32_e32 v49, v49
	v_add_f32_e32 v171, v46, v171
	v_add_f32_e32 v197, v47, v197
	s_waitcnt lgkmcnt(4)
	v_mfma_f32_32x32x16_bf16 v[82:97], v[166:169], v[114:117], v[82:97]
	ds_read_b128 v[188:191], v217 offset:35872
	v_cvt_pk_bf16_f32 v42, v42, v43
	v_add_f32_e32 v171, v48, v171
	v_cvt_pk_bf16_f32 v43, v44, v45
	v_add_f32_e32 v197, v49, v197
	v_cvt_pk_bf16_f32 v44, v46, v47
	v_cvt_pk_bf16_f32 v45, v48, v49
	v_exp_f32_e32 v50, v50
	s_waitcnt lgkmcnt(4)
	v_mfma_f32_32x32x16_bf16 v[66:81], v[172:175], v[118:121], v[66:81]
	ds_read_b128 v[192:195], v217 offset:40480
	v_exp_f32_e32 v51, v51
	v_exp_f32_e32 v52, v52
	v_exp_f32_e32 v53, v53
	s_waitcnt lgkmcnt(4)
	v_mfma_f32_32x32x16_bf16 v[82:97], v[176:179], v[118:121], v[82:97]
	ds_read_b128 v[162:165], v217 offset:35904
	v_add_f32_e32 v171, v50, v171
	v_exp_f32_e32 v54, v54
	v_add_f32_e32 v197, v51, v197
	v_exp_f32_e32 v55, v55
	v_add_f32_e32 v171, v52, v171
	s_waitcnt lgkmcnt(4)
	v_mfma_f32_32x32x16_bf16 v[18:33], v[180:183], v[34:37], v[18:33]
	ds_read_b128 v[166:169], v217 offset:40512
	v_exp_f32_e32 v56, v56
	v_add_f32_e32 v197, v53, v197
	v_exp_f32_e32 v57, v57
	v_add_f32_e32 v171, v54, v171
	v_add_f32_e32 v197, v55, v197
	s_waitcnt lgkmcnt(4)
	v_mfma_f32_32x32x16_bf16 v[2:17], v[184:187], v[34:37], v[2:17]
	ds_read_b128 v[172:175], v217 offset:35936
	v_cvt_pk_bf16_f32 v50, v50, v51
	v_add_f32_e32 v171, v56, v171
	v_cvt_pk_bf16_f32 v51, v52, v53
	v_add_f32_e32 v197, v57, v197
	v_cvt_pk_bf16_f32 v52, v54, v55
	v_cvt_pk_bf16_f32 v53, v56, v57
	v_exp_f32_e32 v58, v58
	s_waitcnt lgkmcnt(4)
	v_mfma_f32_32x32x16_bf16 v[18:33], v[188:191], v[42:45], v[18:33]
	ds_read_b128 v[176:179], v217 offset:40544
	v_exp_f32_e32 v59, v59
	v_exp_f32_e32 v60, v60
	v_exp_f32_e32 v61, v61
	v_add_f32_e32 v171, v58, v171
	s_waitcnt lgkmcnt(4)
	v_mfma_f32_32x32x16_bf16 v[2:17], v[192:195], v[42:45], v[2:17]
	s_waitcnt vmcnt(3)
	ds_write_b128 v228, v[130:133] offset:13312
	ds_write_b128 v238, v[134:137] offset:13312
	ds_write2_b64 v225, v[142:143], v[144:145] offset1:2
	v_exp_f32_e32 v62, v62
	v_add_f32_e32 v197, v59, v197
	v_exp_f32_e32 v63, v63
	v_add_f32_e32 v171, v60, v171
	v_exp_f32_e32 v64, v64
	s_waitcnt lgkmcnt(6)
	v_mfma_f32_32x32x16_bf16 v[18:33], v[162:165], v[50:53], v[18:33]
	v_add_f32_e32 v197, v61, v197
	v_exp_f32_e32 v65, v65
	v_add_f32_e32 v171, v62, v171
	v_add_f32_e32 v197, v63, v197
	v_cvt_pk_bf16_f32 v58, v58, v59
	v_add_f32_e32 v171, v64, v171
	v_cvt_pk_bf16_f32 v59, v60, v61
	s_waitcnt lgkmcnt(5)
	v_mfma_f32_32x32x16_bf16 v[2:17], v[166:169], v[50:53], v[2:17]
	v_add_f32_e32 v197, v65, v197
	v_cvt_pk_bf16_f32 v60, v62, v63
	v_cvt_pk_bf16_f32 v61, v64, v65
	v_max3_f32 v1, v66, v67, v68
	v_max3_f32 v170, v69, v70, v71
	v_max3_f32 v1, v1, v72, v73
	v_max3_f32 v170, v170, v74, v75
	v_max3_f32 v1, v1, v76, v77
	s_waitcnt lgkmcnt(4)
	v_mfma_f32_32x32x16_bf16 v[18:33], v[172:175], v[58:61], v[18:33]
	v_max3_f32 v170, v170, v78, v79
	v_max3_f32 v1, v1, v80, v81
	v_max3_f32 v170, v170, v82, v83
	v_max3_f32 v1, v1, v84, v85
	v_max3_f32 v170, v170, v86, v87
	v_max3_f32 v1, v1, v88, v89
	v_max3_f32 v170, v170, v90, v91
	v_max3_f32 v1, v1, v92, v93
	s_waitcnt lgkmcnt(3)
	v_mfma_f32_32x32x16_bf16 v[2:17], v[176:179], v[58:61], v[2:17]
	v_max3_f32 v170, v170, v94, v95
	v_max3_f32 v1, v1, v96, v97
	v_max_f32_e32 v1, v1, v170
	v_mov_b32_e32 v170, v1
	v_add_f32_e32 v171, v197, v171
	s_nop 0
	v_permlane32_swap_b32_e32 v1, v170
	v_max_f32_e32 v1, v1, v170
	v_cmp_lt_f32_e32 vcc, s93, v1
	s_cbranch_vccnz .Lmf_slow_1
